# P1 V tiles: per-unit B-fragment remap + lane-pair exchange -> V stored as full 128B lines (on top of P4/P5/P6 full-line epilogues, gate tile layout)
# baseline (speedup 1.0000x reference)
.LBB0_141:
	v_bfe_u32 v13, v168, 4, 2
	v_and_b32_e32 v12, 15, v168
	v_lshlrev_b32_e32 v15, 4, v13
	v_lshlrev_b32_e32 v16, 2, v168
	s_and_b32 s8, s6, 3
	v_lshl_or_b32 v169, s7, 6, v12
	v_lshl_or_b32 v12, v12, 6, v15
	s_lshl_b32 s6, s7, 13
	v_and_b32_e32 v16, 32, v16
	s_add_i32 s87, s4, 0x18000
	s_mov_b64 s[18:19], 0x80
	v_bitop3_b32 v181, v12, s6, v16 bitop3:0xde
	v_lshlrev_b32_e32 v12, 6, v168
	s_movk_i32 s6, 0x3c0
	v_lshl_add_u64 v[6:7], v[6:7], 0, s[18:19]
	s_mov_b32 m0, s87
	s_add_i32 s88, s4, 0x1a000
	v_and_or_b32 v12, v12, s6, v15
	s_lshl_b32 s6, s8, 12
	s_waitcnt vmcnt(2)
	s_barrier
	global_load_lds_dwordx4 v[6:7], off
	v_lshl_add_u64 v[4:5], v[4:5], 0, s[18:19]
	s_mov_b32 m0, s88
	s_add_i32 s89, s4, 0x8000
	s_add_i32 s90, s4, 0xa000
	v_bitop3_b32 v12, s6, v12, v16 bitop3:0xf6
	global_load_lds_dwordx4 v[4:5], off
	v_lshl_add_u64 v[0:1], v[0:1], 0, s[18:19]
	s_mov_b32 m0, s89
	s_add_u32 s6, s72, 0x40080
	global_load_lds_dwordx4 v[0:1], off
	v_lshl_add_u64 v[0:1], v[2:3], 0, s[18:19]
	s_mov_b32 m0, s90
	s_addc_u32 s7, s73, 0
	s_add_i32 s91, s4, 0x1c000
	global_load_lds_dwordx4 v[0:1], off
	v_lshl_add_u64 v[0:1], s[6:7], 0, v[172:173]
	s_mov_b32 m0, s91
	s_add_i32 s92, s4, 0x1e000
	global_load_lds_dwordx4 v[0:1], off
	v_lshl_add_u64 v[0:1], s[6:7], 0, v[176:177]
	s_mov_b32 m0, s92
	s_cmpk_lt_u32 s5, 0x100
	global_load_lds_dwordx4 v[0:1], off
	s_cselect_b64 s[20:21], -1, 0
	s_add_u32 s93, s30, 0x9a00000
	s_addc_u32 s94, s31, 0
	v_lshlrev_b32_e32 v0, 2, v13
	s_add_u32 s22, s30, 0x100000
	v_lshl_or_b32 v182, s8, 4, v0
	v_lshlrev_b32_e32 v0, 8, v168
	s_addc_u32 s23, s31, 0
	v_and_b32_e32 v0, 0x38000, v0
	v_lshlrev_b32_e32 v1, 11, v10
	s_add_u32 s24, s30, 0xd00800
	v_or3_b32 v0, v8, v0, v1
	s_addc_u32 s25, s31, 0
	v_add_u32_e32 v184, v0, v9
	v_lshlrev_b32_e32 v0, 4, v11
	s_add_u32 s95, s30, 0xd00000
	v_and_b32_e32 v0, 0x78000, v0
	v_lshlrev_b32_e32 v14, 3, v13
	s_waitcnt vmcnt(6)
	s_addc_u32 s96, s31, 0
	s_lshl_b32 s5, s8, 2
	v_or3_b32 v0, v8, v0, v1
	v_lshl_or_b32 v180, s8, 5, v14
	s_add_u32 s40, s36, s5
	v_add_u32_e32 v186, v0, v9
	v_mbcnt_lo_u32_b32 v0, -1, 0
	v_or_b32_e32 v183, 0xffffe800, v180
	s_mov_b32 s39, 0
	v_cmp_eq_u32_e64 s[6:7], 0, v13
	s_addc_u32 s41, s37, 0
	s_ashr_i32 s97, s33, 31
	s_ashr_i32 s98, s2, 31
	v_mov_b32_e32 v185, v179
	v_mov_b32_e32 v187, v179
	v_mov_b64_e32 v[188:189], 0xa00
	v_mov_b64_e32 v[190:191], 0x9ff
	v_or_b32_e32 v200, 0x10000, v12
	v_add_u32_e32 v201, 0x10400, v12
	v_add_u32_e32 v202, 0x10800, v12
	v_add_u32_e32 v203, 0x10c00, v12
	v_or_b32_e32 v204, 0x14000, v12
	v_add_u32_e32 v205, 0x14400, v12
	v_add_u32_e32 v206, 0x14800, v12
	v_add_u32_e32 v207, 0x14c00, v12
	s_add_i32 s99, s4, 0xc000
	s_add_i32 s79, s4, 0xe000
	v_mov_b32_e32 v208, 0x7f
	v_or_b32_e32 v209, 0x18000, v12
	v_add_u32_e32 v210, 0x18400, v12
	v_add_u32_e32 v211, 0x18800, v12
	v_add_u32_e32 v212, 0x18c00, v12
	v_or_b32_e32 v213, 0x1c000, v12
	v_add_u32_e32 v214, 0x1c400, v12
	v_add_u32_e32 v215, 0x1c800, v12
	v_add_u32_e32 v216, 0x1cc00, v12
	v_mov_b32_e32 v254, v12
	v_and_b32_e32 v255, 0x3000, v12
	v_lshlrev_b32_e32 v255, 1, v255
	v_and_b32_e32 v253, 0xfff, v12
	v_or_b32_e32 v255, v253, v255
	s_mov_b32 s42, 0x3fb8aa3b
	s_mov_b32 s44, 0x3cb8aa3b
	s_mov_b64 s[50:51], 0xa0000
	s_mov_b32 s47, 0xa0000
	s_mov_b64 s[52:53], 0xb0000
	s_mov_b32 s5, 0xb0000
	s_mov_b32 s54, 0x3c800000
	s_mov_b32 s48, 0x1f3c0
	s_mov_b32 s49, 1.0
	s_mov_b64 s[56:57], 0x2000
	s_mov_b64 s[58:59], 0x4000
	s_mov_b64 s[60:61], 0x6000
	v_mbcnt_hi_u32_b32 v217, -1, v0
	s_mov_b32 s46, 0
	s_barrier
	s_branch .LBB0_144

.LBB0_144:
	s_sub_i32 s100, s70, 16
	s_movk_i32 s101, 0x4000
	s_cmp_lt_u32 s100, 8
	s_cselect_b32 s100, 0x1000, s101
	s_cselect_b64 vcc, -1, 0
	s_nop 1
	v_cndmask_b32_e32 v203, v254, v255, vcc
	v_add_u32_e32 v200, 0x10000, v203
	v_add_u32_e32 v201, 0x10400, v203
	v_add_u32_e32 v202, 0x10800, v203
	v_add_u32_e32 v203, 0x10c00, v203
	v_add_u32_e32 v204, s100, v200
	v_add_u32_e32 v205, s100, v201
	v_add_u32_e32 v206, s100, v202
	v_add_u32_e32 v207, s100, v203
	v_add_u32_e32 v209, 0x8000, v200
	v_add_u32_e32 v210, 0x8000, v201
	v_add_u32_e32 v211, 0x8000, v202
	v_add_u32_e32 v212, 0x8000, v203
	v_add_u32_e32 v213, 0x8000, v204
	v_add_u32_e32 v214, 0x8000, v205
	v_add_u32_e32 v215, 0x8000, v206
	v_add_u32_e32 v216, 0x8000, v207
	s_add_i32 s46, s46, 1
	s_mul_i32 s8, s46, s97
	s_mul_hi_u32 s9, s46, s33
	s_add_i32 s9, s9, s8
	s_mul_i32 s8, s46, s33
	s_add_u32 s8, s8, s2
	s_addc_u32 s9, s9, s98
	v_cmp_gt_i64_e32 vcc, s[8:9], v[190:191]
	v_cmp_lt_i64_e64 s[10:11], s[8:9], v[188:189]
	s_cbranch_vccnz .LBB0_146
	s_ashr_i32 s9, s8, 31
	s_lshr_b32 s9, s9, 29
	s_add_i32 s9, s8, s9
	s_ashr_i32 s62, s9, 3
	s_and_b32 s9, s9, -8
	s_sub_i32 s8, s8, s9
	s_cmp_lt_i32 s8, 0
	s_movk_i32 s9, 0x141
	s_cselect_b32 s9, s9, 0x140
	s_mul_i32 s8, s8, s9
	s_add_i32 s8, s8, s62
	s_mul_hi_i32 s9, s8, 0x66666667
	s_lshr_b32 s62, s9, 31
	s_ashr_i32 s9, s9, 5
	s_add_i32 s9, s9, s62
	s_lshl_b32 s63, s9, 1
	s_sub_i32 s62, 64, s63
	s_min_i32 s64, s62, 2
	s_abs_i32 s62, s64
	v_cvt_f32_u32_e32 v0, s62
	s_sub_i32 s66, 0, s62
	s_mulk_i32 s9, 0x50
	s_sub_i32 s8, s8, s9
	v_rcp_iflag_f32_e32 v0, v0
	s_abs_i32 s9, s8
	s_xor_b32 s65, s8, s64
	s_ashr_i32 s65, s65, 31
	v_mul_f32_e32 v0, 0x4f7ffffe, v0
	v_cvt_u32_f32_e32 v0, v0
	s_nop 0
	v_readfirstlane_b32 s67, v0
	s_mul_i32 s66, s66, s67
	s_mul_hi_u32 s66, s67, s66
	s_add_i32 s67, s67, s66
	s_mul_hi_u32 s66, s9, s67
	s_mul_i32 s67, s66, s62
	s_sub_i32 s9, s9, s67
	s_add_i32 s68, s66, 1
	s_sub_i32 s67, s9, s62
	s_cmp_ge_u32 s9, s62
	s_cselect_b32 s66, s68, s66
	s_cselect_b32 s9, s67, s9
	s_add_i32 s67, s66, 1
	s_cmp_ge_u32 s9, s62
	s_cselect_b32 s9, s67, s66
	s_xor_b32 s9, s9, s65
	s_sub_i32 s62, s9, s65
	s_mul_i32 s9, s62, s64
	s_sub_i32 s8, s8, s9
	s_add_i32 s64, s63, s8

.LBB0_155:
	s_andn2_b64 vcc, exec, s[74:75]
	s_cbranch_vccnz .LBB0_157
	s_lshl_b64 s[10:11], s[72:73], 1
	s_add_u32 s10, s26, s10
	v_ashrrev_i32_e32 v193, 31, v192
	s_addc_u32 s11, s27, s11
	v_lshlrev_b64 v[0:1], 12, v[192:193]
	v_lshl_add_u64 v[4:5], s[10:11], 0, v[0:1]
	s_lshl_b32 s38, s70, 9
	v_lshl_add_u64 v[0:1], v[4:5], 0, s[38:39]
	v_lshlrev_b32_e32 v178, 1, v180
	s_movk_i32 s74, 0xe000
	v_lshl_add_u64 v[6:7], v[0:1], 0, v[178:179]
	s_mov_b32 s75, -1
	s_movk_i32 s38, 0xe000
	v_lshl_add_u64 v[8:9], v[6:7], 0, s[74:75]
	v_pk_mul_f32 v[2:3], v[158:159], s[54:55] op_sel_hi:[1,0]
	v_pk_mul_f32 v[0:1], v[156:157], s[54:55] op_sel_hi:[1,0]
	v_pk_mul_f32 v[10:11], v[154:155], s[54:55] op_sel_hi:[1,0]
	v_pk_mul_f32 v[12:13], v[152:153], s[54:55] op_sel_hi:[1,0]
	v_add_co_u32_e32 v6, vcc, s38, v6
	v_cvt_pk_bf16_f32 v220, v0, v1
	v_cvt_pk_bf16_f32 v221, v2, v3
	v_cvt_pk_bf16_f32 v222, v12, v13
	v_cvt_pk_bf16_f32 v223, v10, v11
	v_addc_co_u32_e32 v7, vcc, -1, v7, vcc
	v_pk_mul_f32 v[6:7], v[146:147], s[54:55] op_sel_hi:[1,0]
	v_pk_mul_f32 v[10:11], v[144:145], s[54:55] op_sel_hi:[1,0]
	v_pk_mul_f32 v[2:3], v[150:151], s[54:55] op_sel_hi:[1,0]
	v_pk_mul_f32 v[0:1], v[148:149], s[54:55] op_sel_hi:[1,0]
	s_lshl_b32 s63, s70, 8
	v_cvt_pk_bf16_f32 v0, v0, v1
	v_cvt_pk_bf16_f32 v1, v2, v3
	v_cvt_pk_bf16_f32 v2, v10, v11
	v_cvt_pk_bf16_f32 v3, v6, v7
	v_bfe_u32 v240, v168, 6, 2
	v_and_b32_e32 v237, 1, v169
	v_sub_u32_e32 v237, 0, v237
	v_and_b32_e32 v236, 0xfffff040, v237
	v_lshl_add_u32 v236, v240, 6, v236
	s_mov_b32 s100, 0x1000
	s_mov_b32 s101, 0
	s_mov_b32 vcc_lo, 0x55555555
	s_mov_b32 vcc_hi, 0x55555555
	s_nop 1
	v_cndmask_b32_dpp v228, v0, v220, vcc quad_perm:[0,0,2,2] row_mask:0xf bank_mask:0xf
	v_cndmask_b32_dpp v229, v1, v221, vcc quad_perm:[0,0,2,2] row_mask:0xf bank_mask:0xf
	v_cndmask_b32_dpp v230, v2, v222, vcc quad_perm:[0,0,2,2] row_mask:0xf bank_mask:0xf
	v_cndmask_b32_dpp v231, v3, v223, vcc quad_perm:[0,0,2,2] row_mask:0xf bank_mask:0xf
	s_not_b64 vcc, vcc
	v_cndmask_b32_dpp v0, v220, v0, vcc quad_perm:[1,1,3,3] row_mask:0xf bank_mask:0xf
	v_cndmask_b32_dpp v1, v221, v1, vcc quad_perm:[1,1,3,3] row_mask:0xf bank_mask:0xf
	v_cndmask_b32_dpp v2, v222, v2, vcc quad_perm:[1,1,3,3] row_mask:0xf bank_mask:0xf
	v_cndmask_b32_dpp v3, v223, v3, vcc quad_perm:[1,1,3,3] row_mask:0xf bank_mask:0xf
	s_not_b64 vcc, vcc
	v_lshl_add_u64 v[238:239], v[8:9], 0, v[236:237]
	global_store_dwordx4 v[238:239], v[228:231], off
	v_lshl_add_u64 v[238:239], v[238:239], 0, s[100:101]
	global_store_dwordx4 v[238:239], v[0:3], off
	s_nop 1
	s_add_i32 s38, s63, 0xfffff000
	s_lshl_b64 s[74:75], s[38:39], 1
	v_or_b32_e32 v0, 16, v192
	v_ashrrev_i32_e32 v1, 31, v0
	v_lshlrev_b64 v[0:1], 12, v[0:1]
	v_lshl_add_u64 v[0:1], s[10:11], 0, v[0:1]
	v_lshl_add_u64 v[0:1], v[0:1], 0, s[74:75]
	v_lshl_add_u64 v[6:7], v[0:1], 0, v[178:179]
	v_pk_mul_f32 v[2:3], v[142:143], s[54:55] op_sel_hi:[1,0]
	v_pk_mul_f32 v[0:1], v[140:141], s[54:55] op_sel_hi:[1,0]
	v_pk_mul_f32 v[8:9], v[138:139], s[54:55] op_sel_hi:[1,0]
	v_pk_mul_f32 v[10:11], v[136:137], s[54:55] op_sel_hi:[1,0]
	v_cvt_pk_bf16_f32 v224, v0, v1
	v_cvt_pk_bf16_f32 v225, v2, v3
	v_cvt_pk_bf16_f32 v226, v10, v11
	v_cvt_pk_bf16_f32 v227, v8, v9
	v_pk_mul_f32 v[8:9], v[130:131], s[54:55] op_sel_hi:[1,0]
	v_pk_mul_f32 v[10:11], v[128:129], s[54:55] op_sel_hi:[1,0]
	v_pk_mul_f32 v[2:3], v[134:135], s[54:55] op_sel_hi:[1,0]
	v_pk_mul_f32 v[0:1], v[132:133], s[54:55] op_sel_hi:[1,0]
	s_nop 0
	v_cvt_pk_bf16_f32 v0, v0, v1
	v_cvt_pk_bf16_f32 v1, v2, v3
	v_cvt_pk_bf16_f32 v2, v10, v11
	v_cvt_pk_bf16_f32 v3, v8, v9
	s_mov_b32 vcc_lo, 0x55555555
	s_mov_b32 vcc_hi, 0x55555555
	s_nop 1
	v_cndmask_b32_dpp v232, v0, v224, vcc quad_perm:[0,0,2,2] row_mask:0xf bank_mask:0xf
	v_cndmask_b32_dpp v233, v1, v225, vcc quad_perm:[0,0,2,2] row_mask:0xf bank_mask:0xf
	v_cndmask_b32_dpp v234, v2, v226, vcc quad_perm:[0,0,2,2] row_mask:0xf bank_mask:0xf
	v_cndmask_b32_dpp v235, v3, v227, vcc quad_perm:[0,0,2,2] row_mask:0xf bank_mask:0xf
	s_not_b64 vcc, vcc
	v_cndmask_b32_dpp v0, v224, v0, vcc quad_perm:[1,1,3,3] row_mask:0xf bank_mask:0xf
	v_cndmask_b32_dpp v1, v225, v1, vcc quad_perm:[1,1,3,3] row_mask:0xf bank_mask:0xf
	v_cndmask_b32_dpp v2, v226, v2, vcc quad_perm:[1,1,3,3] row_mask:0xf bank_mask:0xf
	v_cndmask_b32_dpp v3, v227, v3, vcc quad_perm:[1,1,3,3] row_mask:0xf bank_mask:0xf
	s_not_b64 vcc, vcc
	v_lshl_add_u64 v[238:239], v[6:7], 0, v[236:237]
	global_store_dwordx4 v[238:239], v[232:235], off
	v_lshl_add_u64 v[238:239], v[238:239], 0, s[100:101]
	global_store_dwordx4 v[238:239], v[0:3], off
	s_nop 1
	v_pk_mul_f32 v[8:9], v[122:123], s[54:55] op_sel_hi:[1,0]
	v_pk_mul_f32 v[10:11], v[120:121], s[54:55] op_sel_hi:[1,0]
	v_or_b32_e32 v0, 32, v192
	v_ashrrev_i32_e32 v1, 31, v0
	v_lshlrev_b64 v[0:1], 12, v[0:1]
	v_lshl_add_u64 v[0:1], s[10:11], 0, v[0:1]
	v_lshl_add_u64 v[0:1], v[0:1], 0, s[74:75]
	v_lshl_add_u64 v[6:7], v[0:1], 0, v[178:179]
	v_pk_mul_f32 v[2:3], v[126:127], s[54:55] op_sel_hi:[1,0]
	v_pk_mul_f32 v[0:1], v[124:125], s[54:55] op_sel_hi:[1,0]
	s_nop 0
	v_cvt_pk_bf16_f32 v220, v0, v1
	v_cvt_pk_bf16_f32 v221, v2, v3
	v_cvt_pk_bf16_f32 v222, v10, v11
	v_cvt_pk_bf16_f32 v223, v8, v9
	v_pk_mul_f32 v[8:9], v[114:115], s[54:55] op_sel_hi:[1,0]
	v_pk_mul_f32 v[10:11], v[112:113], s[54:55] op_sel_hi:[1,0]
	v_pk_mul_f32 v[2:3], v[118:119], s[54:55] op_sel_hi:[1,0]
	v_pk_mul_f32 v[0:1], v[116:117], s[54:55] op_sel_hi:[1,0]
	s_nop 0
	v_cvt_pk_bf16_f32 v0, v0, v1
	v_cvt_pk_bf16_f32 v1, v2, v3
	v_cvt_pk_bf16_f32 v2, v10, v11
	v_cvt_pk_bf16_f32 v3, v8, v9
	s_mov_b32 vcc_lo, 0x55555555
	s_mov_b32 vcc_hi, 0x55555555
	s_nop 1
	v_cndmask_b32_dpp v228, v0, v220, vcc quad_perm:[0,0,2,2] row_mask:0xf bank_mask:0xf
	v_cndmask_b32_dpp v229, v1, v221, vcc quad_perm:[0,0,2,2] row_mask:0xf bank_mask:0xf
	v_cndmask_b32_dpp v230, v2, v222, vcc quad_perm:[0,0,2,2] row_mask:0xf bank_mask:0xf
	v_cndmask_b32_dpp v231, v3, v223, vcc quad_perm:[0,0,2,2] row_mask:0xf bank_mask:0xf
	s_not_b64 vcc, vcc
	v_cndmask_b32_dpp v0, v220, v0, vcc quad_perm:[1,1,3,3] row_mask:0xf bank_mask:0xf
	v_cndmask_b32_dpp v1, v221, v1, vcc quad_perm:[1,1,3,3] row_mask:0xf bank_mask:0xf
	v_cndmask_b32_dpp v2, v222, v2, vcc quad_perm:[1,1,3,3] row_mask:0xf bank_mask:0xf
	v_cndmask_b32_dpp v3, v223, v3, vcc quad_perm:[1,1,3,3] row_mask:0xf bank_mask:0xf
	s_not_b64 vcc, vcc
	v_lshl_add_u64 v[238:239], v[6:7], 0, v[236:237]
	global_store_dwordx4 v[238:239], v[228:231], off
	v_lshl_add_u64 v[238:239], v[238:239], 0, s[100:101]
	global_store_dwordx4 v[238:239], v[0:3], off
	s_nop 1
	v_pk_mul_f32 v[8:9], v[106:107], s[54:55] op_sel_hi:[1,0]
	v_pk_mul_f32 v[10:11], v[104:105], s[54:55] op_sel_hi:[1,0]
	v_or_b32_e32 v0, 48, v192
	v_ashrrev_i32_e32 v1, 31, v0
	v_lshlrev_b64 v[0:1], 12, v[0:1]
	v_lshl_add_u64 v[0:1], s[10:11], 0, v[0:1]
	v_lshl_add_u64 v[0:1], v[0:1], 0, s[74:75]
	v_lshl_add_u64 v[6:7], v[0:1], 0, v[178:179]
	v_pk_mul_f32 v[2:3], v[110:111], s[54:55] op_sel_hi:[1,0]
	v_pk_mul_f32 v[0:1], v[108:109], s[54:55] op_sel_hi:[1,0]
	s_mov_b64 s[10:11], 0x80000
	v_cvt_pk_bf16_f32 v224, v0, v1
	v_cvt_pk_bf16_f32 v225, v2, v3
	v_cvt_pk_bf16_f32 v226, v10, v11
	v_cvt_pk_bf16_f32 v227, v8, v9
	v_pk_mul_f32 v[8:9], v[98:99], s[54:55] op_sel_hi:[1,0]
	v_pk_mul_f32 v[10:11], v[96:97], s[54:55] op_sel_hi:[1,0]
	v_pk_mul_f32 v[2:3], v[102:103], s[54:55] op_sel_hi:[1,0]
	v_pk_mul_f32 v[0:1], v[100:101], s[54:55] op_sel_hi:[1,0]
	s_nop 0
	v_cvt_pk_bf16_f32 v0, v0, v1
	v_cvt_pk_bf16_f32 v1, v2, v3
	v_cvt_pk_bf16_f32 v2, v10, v11
	v_cvt_pk_bf16_f32 v3, v8, v9
	s_mov_b32 vcc_lo, 0x55555555
	s_mov_b32 vcc_hi, 0x55555555
	s_nop 1
	v_cndmask_b32_dpp v232, v0, v224, vcc quad_perm:[0,0,2,2] row_mask:0xf bank_mask:0xf
	v_cndmask_b32_dpp v233, v1, v225, vcc quad_perm:[0,0,2,2] row_mask:0xf bank_mask:0xf
	v_cndmask_b32_dpp v234, v2, v226, vcc quad_perm:[0,0,2,2] row_mask:0xf bank_mask:0xf
	v_cndmask_b32_dpp v235, v3, v227, vcc quad_perm:[0,0,2,2] row_mask:0xf bank_mask:0xf
	s_not_b64 vcc, vcc
	v_cndmask_b32_dpp v0, v224, v0, vcc quad_perm:[1,1,3,3] row_mask:0xf bank_mask:0xf
	v_cndmask_b32_dpp v1, v225, v1, vcc quad_perm:[1,1,3,3] row_mask:0xf bank_mask:0xf
	v_cndmask_b32_dpp v2, v226, v2, vcc quad_perm:[1,1,3,3] row_mask:0xf bank_mask:0xf
	v_cndmask_b32_dpp v3, v227, v3, vcc quad_perm:[1,1,3,3] row_mask:0xf bank_mask:0xf
	s_not_b64 vcc, vcc
	v_lshl_add_u64 v[238:239], v[6:7], 0, v[236:237]
	global_store_dwordx4 v[238:239], v[232:235], off
	v_lshl_add_u64 v[238:239], v[238:239], 0, s[100:101]
	global_store_dwordx4 v[238:239], v[0:3], off
	s_nop 1
	v_pk_mul_f32 v[8:9], v[90:91], s[54:55] op_sel_hi:[1,0]
	v_pk_mul_f32 v[10:11], v[88:89], s[54:55] op_sel_hi:[1,0]
	v_lshl_add_u64 v[0:1], v[4:5], 0, s[74:75]
	v_lshl_add_u64 v[4:5], v[0:1], 0, v[178:179]
	v_lshl_add_u64 v[6:7], v[4:5], 0, s[10:11]
	v_pk_mul_f32 v[2:3], v[94:95], s[54:55] op_sel_hi:[1,0]
	v_pk_mul_f32 v[0:1], v[92:93], s[54:55] op_sel_hi:[1,0]
	s_mov_b32 s10, 0x80000
	v_cvt_pk_bf16_f32 v220, v0, v1
	v_cvt_pk_bf16_f32 v221, v2, v3
	v_cvt_pk_bf16_f32 v223, v8, v9
	v_add_co_u32_e32 v8, vcc, s10, v4
	v_cvt_pk_bf16_f32 v222, v10, v11
	s_nop 0
	v_addc_co_u32_e32 v9, vcc, 0, v5, vcc
	v_pk_mul_f32 v[8:9], v[82:83], s[54:55] op_sel_hi:[1,0]
	v_pk_mul_f32 v[10:11], v[80:81], s[54:55] op_sel_hi:[1,0]
	v_pk_mul_f32 v[2:3], v[86:87], s[54:55] op_sel_hi:[1,0]
	v_pk_mul_f32 v[0:1], v[84:85], s[54:55] op_sel_hi:[1,0]
	s_mov_b64 s[10:11], 0x90000
	v_cvt_pk_bf16_f32 v0, v0, v1
	v_cvt_pk_bf16_f32 v1, v2, v3
	v_cvt_pk_bf16_f32 v2, v10, v11
	v_cvt_pk_bf16_f32 v3, v8, v9
	s_mov_b32 vcc_lo, 0x55555555
	s_mov_b32 vcc_hi, 0x55555555
	s_nop 1
	v_cndmask_b32_dpp v228, v0, v220, vcc quad_perm:[0,0,2,2] row_mask:0xf bank_mask:0xf
	v_cndmask_b32_dpp v229, v1, v221, vcc quad_perm:[0,0,2,2] row_mask:0xf bank_mask:0xf
	v_cndmask_b32_dpp v230, v2, v222, vcc quad_perm:[0,0,2,2] row_mask:0xf bank_mask:0xf
	v_cndmask_b32_dpp v231, v3, v223, vcc quad_perm:[0,0,2,2] row_mask:0xf bank_mask:0xf
	s_not_b64 vcc, vcc
	v_cndmask_b32_dpp v0, v220, v0, vcc quad_perm:[1,1,3,3] row_mask:0xf bank_mask:0xf
	v_cndmask_b32_dpp v1, v221, v1, vcc quad_perm:[1,1,3,3] row_mask:0xf bank_mask:0xf
	v_cndmask_b32_dpp v2, v222, v2, vcc quad_perm:[1,1,3,3] row_mask:0xf bank_mask:0xf
	v_cndmask_b32_dpp v3, v223, v3, vcc quad_perm:[1,1,3,3] row_mask:0xf bank_mask:0xf
	s_not_b64 vcc, vcc
	v_lshl_add_u64 v[238:239], v[6:7], 0, v[236:237]
	global_store_dwordx4 v[238:239], v[228:231], off
	v_lshl_add_u64 v[238:239], v[238:239], 0, s[100:101]
	global_store_dwordx4 v[238:239], v[0:3], off
	s_nop 1
	v_lshl_add_u64 v[6:7], v[4:5], 0, s[10:11]
	v_pk_mul_f32 v[8:9], v[74:75], s[54:55] op_sel_hi:[1,0]
	v_pk_mul_f32 v[2:3], v[78:79], s[54:55] op_sel_hi:[1,0]
	v_pk_mul_f32 v[0:1], v[76:77], s[54:55] op_sel_hi:[1,0]
	s_mov_b32 s10, 0x90000
	v_pk_mul_f32 v[10:11], v[72:73], s[54:55] op_sel_hi:[1,0]
	v_cvt_pk_bf16_f32 v224, v0, v1
	v_cvt_pk_bf16_f32 v225, v2, v3
	v_cvt_pk_bf16_f32 v227, v8, v9
	v_add_co_u32_e32 v8, vcc, s10, v4
	v_cvt_pk_bf16_f32 v226, v10, v11
	s_nop 0
	v_addc_co_u32_e32 v9, vcc, 0, v5, vcc
	v_pk_mul_f32 v[8:9], v[66:67], s[54:55] op_sel_hi:[1,0]
	v_pk_mul_f32 v[10:11], v[64:65], s[54:55] op_sel_hi:[1,0]
	v_pk_mul_f32 v[2:3], v[70:71], s[54:55] op_sel_hi:[1,0]
	v_pk_mul_f32 v[0:1], v[68:69], s[54:55] op_sel_hi:[1,0]
	s_nop 0
	v_cvt_pk_bf16_f32 v0, v0, v1
	v_cvt_pk_bf16_f32 v1, v2, v3
	v_cvt_pk_bf16_f32 v2, v10, v11
	v_cvt_pk_bf16_f32 v3, v8, v9
	s_mov_b32 vcc_lo, 0x55555555
	s_mov_b32 vcc_hi, 0x55555555
	s_nop 1
	v_cndmask_b32_dpp v232, v0, v224, vcc quad_perm:[0,0,2,2] row_mask:0xf bank_mask:0xf
	v_cndmask_b32_dpp v233, v1, v225, vcc quad_perm:[0,0,2,2] row_mask:0xf bank_mask:0xf
	v_cndmask_b32_dpp v234, v2, v226, vcc quad_perm:[0,0,2,2] row_mask:0xf bank_mask:0xf
	v_cndmask_b32_dpp v235, v3, v227, vcc quad_perm:[0,0,2,2] row_mask:0xf bank_mask:0xf
	s_not_b64 vcc, vcc
	v_cndmask_b32_dpp v0, v224, v0, vcc quad_perm:[1,1,3,3] row_mask:0xf bank_mask:0xf
	v_cndmask_b32_dpp v1, v225, v1, vcc quad_perm:[1,1,3,3] row_mask:0xf bank_mask:0xf
	v_cndmask_b32_dpp v2, v226, v2, vcc quad_perm:[1,1,3,3] row_mask:0xf bank_mask:0xf
	v_cndmask_b32_dpp v3, v227, v3, vcc quad_perm:[1,1,3,3] row_mask:0xf bank_mask:0xf
	s_not_b64 vcc, vcc
	v_lshl_add_u64 v[238:239], v[6:7], 0, v[236:237]
	global_store_dwordx4 v[238:239], v[232:235], off
	v_lshl_add_u64 v[238:239], v[238:239], 0, s[100:101]
	global_store_dwordx4 v[238:239], v[0:3], off
	s_nop 1
	v_pk_mul_f32 v[8:9], v[58:59], s[54:55] op_sel_hi:[1,0]
	v_pk_mul_f32 v[10:11], v[56:57], s[54:55] op_sel_hi:[1,0]
	v_pk_mul_f32 v[2:3], v[62:63], s[54:55] op_sel_hi:[1,0]
	v_pk_mul_f32 v[0:1], v[60:61], s[54:55] op_sel_hi:[1,0]
	v_lshl_add_u64 v[6:7], v[4:5], 0, s[50:51]
	v_cvt_pk_bf16_f32 v220, v0, v1
	v_cvt_pk_bf16_f32 v221, v2, v3
	v_cvt_pk_bf16_f32 v223, v8, v9
	v_add_co_u32_e32 v8, vcc, s47, v4
	v_cvt_pk_bf16_f32 v222, v10, v11
	s_nop 0
	v_addc_co_u32_e32 v9, vcc, 0, v5, vcc
	v_pk_mul_f32 v[8:9], v[50:51], s[54:55] op_sel_hi:[1,0]
	v_pk_mul_f32 v[10:11], v[48:49], s[54:55] op_sel_hi:[1,0]
	v_pk_mul_f32 v[2:3], v[54:55], s[54:55] op_sel_hi:[1,0]
	v_pk_mul_f32 v[0:1], v[52:53], s[54:55] op_sel_hi:[1,0]
	s_nop 0
	v_cvt_pk_bf16_f32 v0, v0, v1
	v_cvt_pk_bf16_f32 v1, v2, v3
	v_cvt_pk_bf16_f32 v2, v10, v11
	v_cvt_pk_bf16_f32 v3, v8, v9
	s_mov_b32 vcc_lo, 0x55555555
	s_mov_b32 vcc_hi, 0x55555555
	s_nop 1
	v_cndmask_b32_dpp v228, v0, v220, vcc quad_perm:[0,0,2,2] row_mask:0xf bank_mask:0xf
	v_cndmask_b32_dpp v229, v1, v221, vcc quad_perm:[0,0,2,2] row_mask:0xf bank_mask:0xf
	v_cndmask_b32_dpp v230, v2, v222, vcc quad_perm:[0,0,2,2] row_mask:0xf bank_mask:0xf
	v_cndmask_b32_dpp v231, v3, v223, vcc quad_perm:[0,0,2,2] row_mask:0xf bank_mask:0xf
	s_not_b64 vcc, vcc
	v_cndmask_b32_dpp v0, v220, v0, vcc quad_perm:[1,1,3,3] row_mask:0xf bank_mask:0xf
	v_cndmask_b32_dpp v1, v221, v1, vcc quad_perm:[1,1,3,3] row_mask:0xf bank_mask:0xf
	v_cndmask_b32_dpp v2, v222, v2, vcc quad_perm:[1,1,3,3] row_mask:0xf bank_mask:0xf
	v_cndmask_b32_dpp v3, v223, v3, vcc quad_perm:[1,1,3,3] row_mask:0xf bank_mask:0xf
	s_not_b64 vcc, vcc
	v_lshl_add_u64 v[238:239], v[6:7], 0, v[236:237]
	global_store_dwordx4 v[238:239], v[228:231], off
	v_lshl_add_u64 v[238:239], v[238:239], 0, s[100:101]
	global_store_dwordx4 v[238:239], v[0:3], off
	s_nop 1
	v_lshl_add_u64 v[6:7], v[4:5], 0, s[52:53]
	v_pk_mul_f32 v[8:9], v[42:43], s[54:55] op_sel_hi:[1,0]
	v_pk_mul_f32 v[2:3], v[46:47], s[54:55] op_sel_hi:[1,0]
	v_pk_mul_f32 v[0:1], v[44:45], s[54:55] op_sel_hi:[1,0]
	v_pk_mul_f32 v[10:11], v[40:41], s[54:55] op_sel_hi:[1,0]
	v_add_co_u32_e32 v4, vcc, s5, v4
	v_cvt_pk_bf16_f32 v224, v0, v1
	v_cvt_pk_bf16_f32 v225, v2, v3
	v_cvt_pk_bf16_f32 v226, v10, v11
	v_cvt_pk_bf16_f32 v227, v8, v9
	v_addc_co_u32_e32 v5, vcc, 0, v5, vcc
	v_pk_mul_f32 v[4:5], v[34:35], s[54:55] op_sel_hi:[1,0]
	v_pk_mul_f32 v[8:9], v[32:33], s[54:55] op_sel_hi:[1,0]
	v_pk_mul_f32 v[2:3], v[38:39], s[54:55] op_sel_hi:[1,0]
	v_pk_mul_f32 v[0:1], v[36:37], s[54:55] op_sel_hi:[1,0]
	s_nop 0
	v_cvt_pk_bf16_f32 v0, v0, v1
	v_cvt_pk_bf16_f32 v1, v2, v3
	v_cvt_pk_bf16_f32 v2, v8, v9
	v_cvt_pk_bf16_f32 v3, v4, v5
	s_mov_b32 vcc_lo, 0x55555555
	s_mov_b32 vcc_hi, 0x55555555
	s_nop 1
	v_cndmask_b32_dpp v232, v0, v224, vcc quad_perm:[0,0,2,2] row_mask:0xf bank_mask:0xf
	v_cndmask_b32_dpp v233, v1, v225, vcc quad_perm:[0,0,2,2] row_mask:0xf bank_mask:0xf
	v_cndmask_b32_dpp v234, v2, v226, vcc quad_perm:[0,0,2,2] row_mask:0xf bank_mask:0xf
	v_cndmask_b32_dpp v235, v3, v227, vcc quad_perm:[0,0,2,2] row_mask:0xf bank_mask:0xf
	s_not_b64 vcc, vcc
	v_cndmask_b32_dpp v0, v224, v0, vcc quad_perm:[1,1,3,3] row_mask:0xf bank_mask:0xf
	v_cndmask_b32_dpp v1, v225, v1, vcc quad_perm:[1,1,3,3] row_mask:0xf bank_mask:0xf
	v_cndmask_b32_dpp v2, v226, v2, vcc quad_perm:[1,1,3,3] row_mask:0xf bank_mask:0xf
	v_cndmask_b32_dpp v3, v227, v3, vcc quad_perm:[1,1,3,3] row_mask:0xf bank_mask:0xf
	s_not_b64 vcc, vcc
	v_lshl_add_u64 v[238:239], v[6:7], 0, v[236:237]
	global_store_dwordx4 v[238:239], v[232:235], off
	v_lshl_add_u64 v[238:239], v[238:239], 0, s[100:101]
	global_store_dwordx4 v[238:239], v[0:3], off
	s_nop 1
